# EpiRes GEMM phases visit the XCDs two row-panel groups in swapped order (pm^8) so freshly written panels are consumed first; plus scalar phase header
# baseline (speedup 1.0000x reference)
;     __device__ bool next(int i, Unit& u) const {
;         const long L = (long)i * G + c; if (L >= nwg) return false;
;         int wgid = (int)L; { const int q = nwg / NXCD, r = nwg % NXCD, xcd = wgid % NXCD, off = wgid / NXCD; wgid = (xcd < r ? xcd * (q + 1) : r * (q + 1) + (xcd - r) * q) + off; }
;         const int nig = WGM * nN, gid = wgid / nig, fm = gid * WGM, gsz = (nM - fm) < WGM ? (nM - fm) : WGM;
;         u.pm = fm + ((wgid % nig) % gsz); u.pn = (wgid % nig) / gsz; return true;
; template <class Epi, bool ALIGN_EPI>
; __device__ __forceinline__ void gemm_phase(LAS unsigned char* lds, const Gemm g, const StaticOrder& S, const Epi& E, const int tid) {
;     ...
;     if (!S.next(0, cur)) return;
.LBB0_258:
	s_and_b64 vcc, exec, s[10:11]
	s_cbranch_vccz .LBB0_292
	s_and_b64 vcc, exec, s[8:9]
	v_readfirstlane_b32 s46, v170
	s_cbranch_vccnz .LBB0_261
	s_lshl_b32 s13, s7, 3
	v_cvt_f32_u32_e32 v0, s13
	s_ashr_i32 s11, s0, 31
	s_lshr_b32 s11, s11, 29
	s_add_i32 s11, s0, s11
	v_rcp_iflag_f32_e32 v0, v0
	s_ashr_i32 s12, s11, 3
	s_and_b32 s11, s11, -8
	s_sub_i32 s11, s0, s11
	v_mul_f32_e32 v0, 0x4f7ffffe, v0
	v_cvt_u32_f32_e32 v0, v0
	s_lshl_b32 s10, s7, 4
	s_lshr_b32 s14, s11, 31
	s_or_b32 s10, s10, s14
	s_waitcnt lgkmcnt(0)
	v_mov_b32_e32 v1, s11
	v_mul_i32_i24_e32 v1, s10, v1
	s_sub_i32 s14, 0, s13
	v_readfirstlane_b32 s15, v0
	v_readfirstlane_b32 s10, v1
	s_mul_i32 s14, s14, s15
	s_add_i32 s10, s10, s12
	s_mul_hi_u32 s14, s15, s14
	s_abs_i32 s12, s10
	s_add_i32 s15, s15, s14
	s_mul_hi_u32 s14, s12, s15
	s_mul_i32 s15, s14, s13
	s_sub_i32 s12, s12, s15
	s_ashr_i32 s11, s10, 31
	s_add_i32 s15, s14, 1
	s_sub_i32 s39, s12, s13
	s_cmp_ge_u32 s12, s13
	s_cselect_b32 s14, s15, s14
	s_cselect_b32 s12, s39, s12
	s_add_i32 s15, s14, 1
	s_cmp_ge_u32 s12, s13
	s_cselect_b32 s12, s15, s14
	s_xor_b32 s12, s12, s11
	s_sub_i32 s11, s12, s11
	s_lshl_b32 s12, s11, 3
	s_sub_i32 s14, 0x80, s12
	s_min_i32 s14, s14, 8
	s_mul_i32 s11, s11, s13
	s_sext_i32_i16 s13, s14
	v_cvt_f32_i32_e32 v0, s13
	s_sub_i32 s15, s10, s11
	s_sext_i32_i16 s10, s15
	v_cvt_f32_i32_e32 v1, s10
	v_rcp_iflag_f32_e32 v2, v0
	s_xor_b32 s10, s10, s13
	s_ashr_i32 s10, s10, 30
	s_or_b32 s13, s10, 1
	v_mul_f32_e32 v2, v1, v2
	v_trunc_f32_e32 v2, v2
	v_fma_f32 v1, -v2, v0, v1
	v_cvt_i32_f32_e32 v2, v2
	v_cmp_ge_f32_e64 s[10:11], |v1|, |v0|
	s_and_b64 s[10:11], s[10:11], exec
	s_cselect_b32 s10, s13, 0
	v_readfirstlane_b32 s11, v2
	s_add_i32 s10, s11, s10
	s_mul_i32 s11, s10, s14
	s_sub_i32 s11, s15, s11
	s_sext_i32_i16 s11, s11
	s_add_i32 s67, s12, s11
	s_xor_b32 s67, s67, 8
	s_sext_i32_i16 s66, s10

;     __device__ bool next(int i, Unit& u) const {
;         const long L = (long)i * G + c; if (L >= nwg) return false;
;         int wgid = (int)L; { const int q = nwg / NXCD, r = nwg % NXCD, xcd = wgid % NXCD, off = wgid / NXCD; wgid = (xcd < r ? xcd * (q + 1) : r * (q + 1) + (xcd - r) * q) + off; }
;         const int nig = WGM * nN, gid = wgid / nig, fm = gid * WGM, gsz = (nM - fm) < WGM ? (nM - fm) : WGM;
;         u.pm = fm + ((wgid % nig) % gsz); u.pn = (wgid % nig) / gsz; return true;
; template <class Epi, bool ALIGN_EPI>
; __device__ __forceinline__ void gemm_phase(LAS unsigned char* lds, const Gemm g, const StaticOrder& S, const Epi& E, const int tid) {
;     ...
;         const bool has_next = S.next(ui + 1, nxt);
;         const char* nA = has_next ? (const char*)g.A + (size_t)nxt.pm * tA + (size_t)nxt.pn * g.apn * 2 : cA; const char* nB = has_next ? (const char*)g.Bt + (size_t)nxt.pn * tB : cB;
.LBB0_266:
	s_add_i32 s62, s62, 1
	s_mul_i32 s8, s62, s58
	s_mul_hi_u32 s9, s62, s6
	s_add_i32 s9, s9, s8
	s_mul_i32 s8, s62, s6
	s_add_u32 s12, s8, s0
	s_addc_u32 s13, s9, s59
	s_waitcnt lgkmcnt(0)
	v_mov_b64_e32 v[0:1], s[38:39]
	v_cmp_ge_i64_e64 s[8:9], s[12:13], v[0:1]
	v_cmp_lt_i64_e64 s[10:11], s[12:13], v[0:1]
	s_and_b64 vcc, exec, s[8:9]
	s_cbranch_vccnz .LBB0_268
	s_ashr_i32 s13, s12, 31
	s_lshr_b32 s13, s13, 29
	s_add_i32 s13, s12, s13
	s_ashr_i32 s64, s13, 3
	s_and_b32 s13, s13, -8
	s_sub_i32 s12, s12, s13
	s_lshr_b32 s13, s12, 31
	s_or_b32 s13, s60, s13
	s_mul_i32 s12, s13, s12
	s_add_i32 s12, s12, s64
	s_abs_i32 s64, s12
	s_mul_hi_u32 s65, s64, s63
	s_mul_i32 s68, s65, s61
	s_sub_i32 s64, s64, s68
	s_ashr_i32 s13, s12, 31
	s_add_i32 s68, s65, 1
	s_sub_i32 s69, s64, s61
	s_cmp_ge_u32 s64, s61
	s_cselect_b32 s65, s68, s65
	s_cselect_b32 s64, s69, s64
	s_add_i32 s68, s65, 1
	s_cmp_ge_u32 s64, s61
	s_cselect_b32 s64, s68, s65
	s_xor_b32 s64, s64, s13
	s_sub_i32 s13, s64, s13
	s_lshl_b32 s65, s13, 3
	s_sub_i32 s64, 0x80, s65
	s_min_i32 s68, s64, 8
	s_abs_i32 s64, s68
	v_cvt_f32_u32_e32 v0, s64
	s_sub_i32 s70, 0, s64
	s_mul_i32 s13, s13, s61
	s_sub_i32 s12, s12, s13
	v_rcp_iflag_f32_e32 v0, v0
	s_abs_i32 s69, s12
	s_xor_b32 s13, s12, s68
	s_ashr_i32 s13, s13, 31
	v_mul_f32_e32 v0, 0x4f7ffffe, v0
	v_cvt_u32_f32_e32 v0, v0
	s_nop 0
	v_readfirstlane_b32 s71, v0
	s_mul_i32 s70, s70, s71
	s_mul_hi_u32 s70, s71, s70
	s_add_i32 s71, s71, s70
	s_mul_hi_u32 s70, s69, s71
	s_mul_i32 s71, s70, s64
	s_sub_i32 s69, s69, s71
	s_add_i32 s71, s70, 1
	s_sub_i32 s72, s69, s64
	s_cmp_ge_u32 s69, s64
	s_cselect_b32 s70, s71, s70
	s_cselect_b32 s69, s72, s69
	s_add_i32 s71, s70, 1
	s_cmp_ge_u32 s69, s64
	s_cselect_b32 s64, s71, s70
	s_xor_b32 s64, s64, s13
	s_sub_i32 s64, s64, s13
	s_mul_i32 s13, s64, s68
	s_sub_i32 s12, s12, s13
	s_mov_b32 s72, 0x40000
	s_mov_b64 s[70:71], s[90:91]
	s_add_i32 s65, s12, s65
	s_xor_b32 s65, s65, 8
